# attention unit staging: second K task's loads and the four V loads issued up front with the first K task's (one latency instead of six serial round trips)
# speedup vs baseline: 1.0109x; 1.0028x over previous
.LBB0_268:
	s_lshl_b32 s9, s23, 6
	s_and_b32 s9, s9, 0xf80
	v_readlane_b32 s24, v249, 4
	v_mov_b32_e32 v3, v186
	s_or_b32 s9, s9, s24
	s_and_b32 s8, s23, 1
	s_add_i32 s25, s9, 0xffffff80
	v_lshlrev_b32_e32 v0, 3, v3
	s_cmp_gt_u32 s23, 1
	v_and_b32_e32 v0, 24, v0
	v_ashrrev_i32_e32 v26, 2, v3
	s_movk_i32 s26, 0x7f
	s_cselect_b64 s[36:37], -1, 0
	v_lshlrev_b32_e32 v32, 2, v0
	v_mov_b32_e32 v33, v2
	v_cmp_lt_i32_e32 vcc, s26, v26
	s_lshl_b32 s24, s8, 6
	v_lshl_add_u64 v[22:23], s[38:39], 0, v[32:33]
	v_lshl_add_u64 v[24:25], s[40:41], 0, v[32:33]
	s_or_b64 s[26:27], s[36:37], vcc
	s_waitcnt vmcnt(0)
	v_mov_b32_e32 v4, 0
	v_lshlrev_b32_e32 v0, 1, v0
	v_mov_b32_e32 v10, 0
	v_mov_b32_e32 v11, 0
	v_mov_b32_e32 v12, 0
	v_mov_b32_e32 v13, 0
	v_mov_b32_e32 v6, 0
	v_mov_b32_e32 v7, 0
	v_mov_b32_e32 v8, 0
	v_mov_b32_e32 v9, 0
	v_add_u32_e32 v192, 0x200, v3
	v_ashrrev_i32_e32 v192, 2, v192
	v_add_u32_e32 v193, s25, v192
	v_mov_b64_e32 v[194:195], s[4:5]
	s_lshl_b32 s90, s24, 1
	v_mad_i64_i32 v[194:195], vcc, v193, s61, v[194:195]
	v_mov_b32_e32 v196, v0
	v_mov_b32_e32 v197, v2
	v_lshl_add_u64 v[194:195], v[194:195], 0, s[90:91]
	v_lshl_add_u64 v[194:195], v[194:195], 0, v[196:197]
	global_load_dwordx4 v[200:203], v[194:195], off offset:3072
	global_load_dwordx4 v[204:207], v[194:195], off offset:3136
	v_lshlrev_b32_e32 v196, 5, v193
	v_ashrrev_i32_e32 v197, 31, v196
	v_lshlrev_b64 v[196:197], 2, v[196:197]
	v_lshl_add_u64 v[198:199], v[22:23], 0, v[196:197]
	v_lshl_add_u64 v[196:197], v[24:25], 0, v[196:197]
	global_load_dwordx4 v[208:211], v[198:199], off offset:16
	global_load_dwordx4 v[212:215], v[198:199], off
	global_load_dwordx4 v[216:219], v[196:197], off offset:16
	global_load_dwordx4 v[220:223], v[196:197], off
	v_and_b32_e32 v192, 0xff, v3
	v_add_u32_e32 v194, s25, v192
	v_mul_i32_i24_e32 v194, 0x900, v194
	v_ashrrev_i32_e32 v195, 31, v194
	v_cmp_lt_u32_e32 vcc, 0x7f, v192
	v_lshl_add_u64 v[194:195], v[194:195], 1, s[4:5]
	s_or_b64 s[50:51], s[36:37], vcc
	v_lshl_add_u64 v[194:195], v[194:195], 0, s[90:91]
	v_ashrrev_i32_e32 v196, 8, v3
	v_lshlrev_b32_e32 v196, 4, v196
	v_ashrrev_i32_e32 v197, 31, v196
	v_lshl_add_u64 v[194:195], v[194:195], 0, v[196:197]
	s_and_saveexec_b64 s[50:51], s[50:51]
	global_load_dwordx4 v[224:227], v[194:195], off offset:3328
	global_load_dwordx4 v[228:231], v[194:195], off offset:3360
	global_load_dwordx4 v[232:235], v[194:195], off offset:3392
	global_load_dwordx4 v[236:239], v[194:195], off offset:3424
	s_or_b64 exec, exec, s[50:51]
	s_and_saveexec_b64 s[48:49], s[26:27]
	s_cbranch_execz .LBB0_270
	v_add_u32_e32 v5, s25, v26
	v_mov_b64_e32 v[6:7], s[4:5]
	v_mad_i64_i32 v[6:7], s[26:27], v5, s61, v[6:7]
	s_lshl_b32 s90, s24, 1
	v_lshl_add_u64 v[6:7], v[6:7], 0, s[90:91]
	v_mov_b32_e32 v1, v2
	v_lshl_add_u64 v[6:7], v[6:7], 0, v[0:1]
	global_load_dwordx4 v[14:17], v[6:7], off offset:3072
	global_load_dwordx4 v[18:21], v[6:7], off offset:3136
	v_lshlrev_b32_e32 v6, 5, v5
	v_ashrrev_i32_e32 v7, 31, v6
	v_lshlrev_b64 v[6:7], 2, v[6:7]
	v_lshl_add_u64 v[10:11], v[22:23], 0, v[6:7]
	v_lshl_add_u64 v[34:35], v[24:25], 0, v[6:7]
	global_load_dwordx4 v[6:9], v[10:11], off offset:16
	global_load_dwordx4 v[28:31], v[10:11], off
	s_nop 0
	global_load_dwordx4 v[10:13], v[34:35], off offset:16
	s_nop 0
	global_load_dwordx4 v[34:37], v[34:35], off
	s_waitcnt vmcnt(5)
	v_lshlrev_b32_e32 v39, 16, v14
	s_waitcnt vmcnt(4)
	v_lshlrev_b32_e32 v38, 16, v18
	s_waitcnt vmcnt(2)
	v_mov_b32_e32 v41, v28
	s_waitcnt vmcnt(0)
	v_mov_b32_e32 v40, v34
	v_pk_mul_f32 v[40:41], v[40:41], v[38:39]
	s_nop 0
	v_sub_f32_e32 v5, v41, v40
	v_mov_b32_e32 v40, v28
	v_mov_b32_e32 v41, v34
	v_pk_mul_f32 v[38:39], v[40:41], v[38:39]
	v_mov_b32_e32 v28, v35
	v_add_f32_e32 v1, v38, v39
	v_and_b32_e32 v39, 0xffff0000, v14
	v_and_b32_e32 v38, 0xffff0000, v18
	v_mov_b32_e32 v34, v29
	v_pk_mul_f32 v[40:41], v[28:29], v[38:39]
	v_pk_mul_f32 v[28:29], v[34:35], v[38:39]
	v_mov_b32_e32 v34, v36
	v_add_f32_e32 v33, v28, v29
	v_lshlrev_b32_e32 v29, 16, v15
	v_lshlrev_b32_e32 v28, 16, v19
	v_mov_b32_e32 v35, v30
	v_pk_mul_f32 v[34:35], v[34:35], v[28:29]
	v_and_b32_e32 v15, 0xffff0000, v15
	v_sub_f32_e32 v38, v35, v34
	v_mov_b32_e32 v34, v30
	v_mov_b32_e32 v35, v36
	v_and_b32_e32 v14, 0xffff0000, v19
	v_mov_b32_e32 v30, v37
	v_mov_b32_e32 v36, v31
	v_pk_mul_f32 v[28:29], v[34:35], v[28:29]
	v_pk_mul_f32 v[18:19], v[30:31], v[14:15]
	v_pk_mul_f32 v[14:15], v[36:37], v[14:15]
	v_add_f32_e32 v28, v28, v29
	v_sub_f32_e32 v29, v19, v18
	v_add_f32_e32 v30, v14, v15
	v_lshlrev_b32_e32 v15, 16, v16
	v_lshlrev_b32_e32 v14, 16, v20
	v_mov_b32_e32 v18, v10
	v_mov_b32_e32 v19, v6
	v_pk_mul_f32 v[18:19], v[18:19], v[14:15]
	v_sub_f32_e32 v27, v41, v40
	v_sub_f32_e32 v31, v19, v18
	v_mov_b32_e32 v18, v6
	v_mov_b32_e32 v19, v10
	v_pk_mul_f32 v[14:15], v[18:19], v[14:15]
	v_mov_b32_e32 v6, v11
	v_add_f32_e32 v34, v14, v15
	v_and_b32_e32 v15, 0xffff0000, v16
	v_and_b32_e32 v14, 0xffff0000, v20
	v_mov_b32_e32 v10, v7
	v_pk_mul_f32 v[18:19], v[6:7], v[14:15]
	v_pk_mul_f32 v[6:7], v[10:11], v[14:15]
	v_mov_b32_e32 v10, v12
	v_add_f32_e32 v14, v6, v7
	v_lshlrev_b32_e32 v7, 16, v17
	v_lshlrev_b32_e32 v6, 16, v21
	v_mov_b32_e32 v11, v8
	v_pk_mul_f32 v[10:11], v[10:11], v[6:7]
	v_sub_f32_e32 v16, v19, v18
	v_sub_f32_e32 v15, v11, v10
	v_mov_b32_e32 v10, v8
	v_mov_b32_e32 v11, v12
	v_pk_mul_f32 v[6:7], v[10:11], v[6:7]
	v_mov_b32_e32 v8, v13
	v_add_f32_e32 v18, v6, v7
	v_and_b32_e32 v7, 0xffff0000, v17
	v_and_b32_e32 v6, 0xffff0000, v21
	v_mov_b32_e32 v12, v9
	v_pk_mul_f32 v[10:11], v[8:9], v[6:7]
	v_pk_mul_f32 v[6:7], v[12:13], v[6:7]
	v_sub_f32_e32 v10, v11, v10
	v_add_f32_e32 v13, v6, v7
	v_cvt_pk_bf16_f32 v6, v5, v27
	v_cvt_pk_bf16_f32 v7, v38, v29
	v_cvt_pk_bf16_f32 v8, v31, v16
	v_cvt_pk_bf16_f32 v9, v15, v10
	v_cvt_pk_bf16_f32 v10, v1, v33
	v_cvt_pk_bf16_f32 v11, v28, v30
	v_cvt_pk_bf16_f32 v12, v34, v14
	v_cvt_pk_bf16_f32 v13, v18, v13
.LBB0_270:
	s_or_b64 exec, exec, s[48:49]
	s_movk_i32 s26, 0x90
	v_add_u32_e32 v20, 0x200, v3
	v_mul_lo_u32 v50, v26, s26
	v_ashrrev_i32_e32 v21, 2, v20
	s_movk_i32 s26, 0x7f
	v_add3_u32 v1, 0, v50, v0
	v_cmp_lt_i32_e32 vcc, s26, v21
	ds_write_b128 v1, v[6:9]
	ds_write_b128 v1, v[10:13] offset:64
	s_or_b64 s[26:27], s[36:37], vcc
	v_mov_b32_e32 v5, 0
	v_mov_b32_e32 v6, 0
	v_mov_b32_e32 v7, 0
	v_mov_b32_e32 v8, 0
	v_mov_b32_e32 v9, 0
	v_mov_b32_e32 v10, 0
	v_mov_b32_e32 v11, 0
	s_and_saveexec_b64 s[48:49], s[26:27]
	s_cbranch_execz .LBB0_272
	s_waitcnt vmcnt(4)
	v_mov_b32_e32 v12, v200
	v_mov_b32_e32 v13, v201
	v_mov_b32_e32 v14, v202
	v_mov_b32_e32 v15, v203
	v_mov_b32_e32 v16, v204
	v_mov_b32_e32 v17, v205
	v_mov_b32_e32 v18, v206
	v_mov_b32_e32 v19, v207
	v_mov_b32_e32 v4, v208
	v_mov_b32_e32 v5, v209
	v_mov_b32_e32 v6, v210
	v_mov_b32_e32 v7, v211
	v_mov_b32_e32 v28, v212
	v_mov_b32_e32 v29, v213
	v_mov_b32_e32 v30, v214
	v_mov_b32_e32 v31, v215
	v_mov_b32_e32 v8, v216
	v_mov_b32_e32 v9, v217
	v_mov_b32_e32 v10, v218
	v_mov_b32_e32 v11, v219
	v_mov_b32_e32 v34, v220
	v_mov_b32_e32 v35, v221
	v_mov_b32_e32 v36, v222
	v_mov_b32_e32 v37, v223
	s_waitcnt vmcnt(5)
	v_lshlrev_b32_e32 v25, 16, v12
	s_waitcnt vmcnt(4)
	v_lshlrev_b32_e32 v24, 16, v16
	s_waitcnt vmcnt(2)
	v_mov_b32_e32 v23, v28
	v_mov_b32_e32 v38, v28
	s_waitcnt vmcnt(0)
	v_mov_b32_e32 v22, v34
	v_mov_b32_e32 v39, v34
	v_pk_mul_f32 v[22:23], v[22:23], v[24:25]
	v_pk_mul_f32 v[24:25], v[38:39], v[24:25]
	v_mov_b32_e32 v28, v35
	v_add_f32_e32 v1, v24, v25
	v_and_b32_e32 v25, 0xffff0000, v12
	v_and_b32_e32 v24, 0xffff0000, v16
	v_mov_b32_e32 v34, v29
	v_pk_mul_f32 v[38:39], v[28:29], v[24:25]
	v_pk_mul_f32 v[24:25], v[34:35], v[24:25]
	v_mov_b32_e32 v28, v36
	v_add_f32_e32 v27, v24, v25
	v_lshlrev_b32_e32 v25, 16, v13
	v_lshlrev_b32_e32 v24, 16, v17
	v_mov_b32_e32 v29, v30
	v_pk_mul_f32 v[28:29], v[28:29], v[24:25]
	v_and_b32_e32 v13, 0xffff0000, v13
	v_sub_f32_e32 v33, v29, v28
	v_mov_b32_e32 v28, v30
	v_mov_b32_e32 v29, v36
	v_and_b32_e32 v12, 0xffff0000, v17
	v_mov_b32_e32 v30, v37
	v_mov_b32_e32 v36, v31
	v_pk_mul_f32 v[24:25], v[28:29], v[24:25]
	v_pk_mul_f32 v[16:17], v[30:31], v[12:13]
	v_pk_mul_f32 v[12:13], v[36:37], v[12:13]
	v_add_f32_e32 v24, v24, v25
	v_sub_f32_e32 v25, v17, v16
	v_add_f32_e32 v28, v12, v13
	v_lshlrev_b32_e32 v13, 16, v14
	v_lshlrev_b32_e32 v12, 16, v18
	v_mov_b32_e32 v16, v8
	v_mov_b32_e32 v17, v4
	v_pk_mul_f32 v[16:17], v[16:17], v[12:13]
	v_sub_f32_e32 v22, v23, v22
	v_sub_f32_e32 v29, v17, v16
	v_mov_b32_e32 v16, v4
	v_mov_b32_e32 v17, v8
	v_pk_mul_f32 v[12:13], v[16:17], v[12:13]
	v_mov_b32_e32 v4, v9
	v_add_f32_e32 v30, v12, v13
	v_and_b32_e32 v13, 0xffff0000, v14
	v_and_b32_e32 v12, 0xffff0000, v18
	v_mov_b32_e32 v8, v5
	v_pk_mul_f32 v[16:17], v[4:5], v[12:13]
	v_pk_mul_f32 v[4:5], v[8:9], v[12:13]
	v_mov_b32_e32 v8, v10
	v_add_f32_e32 v12, v4, v5
	v_lshlrev_b32_e32 v5, 16, v15
	v_lshlrev_b32_e32 v4, 16, v19
	v_mov_b32_e32 v9, v6
	v_pk_mul_f32 v[8:9], v[8:9], v[4:5]
	v_sub_f32_e32 v14, v17, v16
	v_sub_f32_e32 v13, v9, v8
	v_mov_b32_e32 v8, v6
	v_mov_b32_e32 v9, v10
	v_pk_mul_f32 v[4:5], v[8:9], v[4:5]
	v_mov_b32_e32 v6, v11
	v_add_f32_e32 v16, v4, v5
	v_and_b32_e32 v5, 0xffff0000, v15
	v_and_b32_e32 v4, 0xffff0000, v19
	v_mov_b32_e32 v10, v7
	v_pk_mul_f32 v[8:9], v[6:7], v[4:5]
	v_pk_mul_f32 v[4:5], v[10:11], v[4:5]
	v_sub_f32_e32 v6, v9, v8
	v_add_f32_e32 v7, v4, v5
	v_sub_f32_e32 v23, v39, v38
	v_cvt_pk_bf16_f32 v8, v22, v23
	v_cvt_pk_bf16_f32 v9, v33, v25
	v_cvt_pk_bf16_f32 v10, v29, v14
	v_cvt_pk_bf16_f32 v11, v13, v6
	v_cvt_pk_bf16_f32 v4, v1, v27
	v_cvt_pk_bf16_f32 v5, v24, v28
	v_cvt_pk_bf16_f32 v6, v30, v12
	v_cvt_pk_bf16_f32 v7, v16, v7
.LBB0_272:
	s_or_b64 exec, exec, s[48:49]
	s_movk_i32 s26, 0x90
	v_mul_lo_u32 v1, v21, s26
	v_add3_u32 v1, 0, v1, v0
	ds_write_b128 v1, v[8:11]
	ds_write_b128 v1, v[4:7] offset:64
	v_and_b32_e32 v1, 0xff, v3
	v_add_u32_e32 v4, s25, v1
	v_mul_i32_i24_e32 v4, 0x900, v4
	s_movk_i32 s26, 0x7f
	v_ashrrev_i32_e32 v5, 31, v4
	v_cmp_lt_u32_e32 vcc, s26, v1
	v_lshl_add_u64 v[4:5], v[4:5], 1, s[4:5]
	s_lshl_b32 s90, s24, 1
	s_or_b64 s[48:49], s[36:37], vcc
	v_lshl_add_u64 v[10:11], v[4:5], 0, s[90:91]
	v_ashrrev_i32_e32 v5, 8, v3
	v_mov_b32_e32 v4, 0
	v_mov_b32_e32 v6, 0
	v_mov_b32_e32 v7, 0
	v_mov_b32_e32 v8, 0
	v_mov_b32_e32 v9, 0
	s_and_saveexec_b64 s[50:51], s[48:49]
	s_cbranch_execz .LBB0_274
	s_waitcnt vmcnt(0)
	v_mov_b32_e32 v6, v224
	v_mov_b32_e32 v7, v225
	v_mov_b32_e32 v8, v226
	v_mov_b32_e32 v9, v227
.LBB0_274:
	s_or_b64 exec, exec, s[50:51]
	v_lshl_add_u32 v34, v1, 1, 0
	s_movk_i32 s24, 0x1080
	v_mad_i32_i24 v1, v5, s24, v34
	s_waitcnt vmcnt(0)
	ds_write_b16 v1, v6 offset:36864
	ds_write_b16_d16_hi v1, v6 offset:37392
	ds_write_b16 v1, v7 offset:37920
	ds_write_b16_d16_hi v1, v7 offset:38448
	ds_write_b16 v1, v8 offset:38976
	ds_write_b16_d16_hi v1, v8 offset:39504
	ds_write_b16 v1, v9 offset:40032
	ds_write_b16_d16_hi v1, v9 offset:40560
	v_ashrrev_i32_e32 v1, 8, v20
	v_mov_b32_e32 v5, 0
	v_mov_b32_e32 v6, 0
	v_mov_b32_e32 v7, 0
	s_and_saveexec_b64 s[50:51], s[48:49]
	s_cbranch_execz .LBB0_276
	v_mov_b32_e32 v4, v228
	v_mov_b32_e32 v5, v229
	v_mov_b32_e32 v6, v230
	v_mov_b32_e32 v7, v231
.LBB0_276:
	s_or_b64 exec, exec, s[50:51]
	v_mad_i32_i24 v1, v1, s24, v34
	s_waitcnt vmcnt(0)
	ds_write_b16 v1, v4 offset:36864
	ds_write_b16_d16_hi v1, v4 offset:37392
	ds_write_b16 v1, v5 offset:37920
	ds_write_b16_d16_hi v1, v5 offset:38448
	ds_write_b16 v1, v6 offset:38976
	ds_write_b16_d16_hi v1, v6 offset:39504
	ds_write_b16 v1, v7 offset:40032
	ds_write_b16_d16_hi v1, v7 offset:40560
	v_add_u32_e32 v1, 0x400, v3
	v_ashrrev_i32_e32 v1, 8, v1
	v_mov_b32_e32 v20, 0
	v_mov_b32_e32 v4, 0
	v_mov_b32_e32 v5, 0
	v_mov_b32_e32 v6, 0
	v_mov_b32_e32 v7, 0
	s_and_saveexec_b64 s[50:51], s[48:49]
	s_cbranch_execz .LBB0_278
	v_mov_b32_e32 v4, v232
	v_mov_b32_e32 v5, v233
	v_mov_b32_e32 v6, v234
	v_mov_b32_e32 v7, v235
.LBB0_278:
	s_or_b64 exec, exec, s[50:51]
	v_mad_i32_i24 v1, v1, s24, v34
	s_waitcnt vmcnt(0)
	ds_write_b16 v1, v4 offset:36864
	ds_write_b16_d16_hi v1, v4 offset:37392
	ds_write_b16 v1, v5 offset:37920
	ds_write_b16_d16_hi v1, v5 offset:38448
	ds_write_b16 v1, v6 offset:38976
	ds_write_b16_d16_hi v1, v6 offset:39504
	ds_write_b16 v1, v7 offset:40032
	ds_write_b16_d16_hi v1, v7 offset:40560
	v_add_u32_e32 v1, 0x600, v3
	v_ashrrev_i32_e32 v35, 8, v1
	v_mov_b32_e32 v21, 0
	v_mov_b32_e32 v22, 0
	v_mov_b32_e32 v23, 0
	s_and_saveexec_b64 s[50:51], s[48:49]
	s_cbranch_execz .LBB0_280
	v_mov_b32_e32 v20, v236
	v_mov_b32_e32 v21, v237
	v_mov_b32_e32 v22, v238
	v_mov_b32_e32 v23, v239
